# baseline (speedup 1.0000x reference)
; DEV void gemm_tile(const u16* __restrict__ A, const u16* __restrict__ Bt, u16* __restrict__ C, int N, int K,
;                    int brow, int bcol, unsigned char* smem, int epi, const GateEpi& ge) {
;     ...
;     const int pm = brow >> 8, pn = bcol >> 8;
;     float w0[2], w1[2], w2[2], bs[2];
; #pragma unroll
;     for (int n = 0; n < 2; ++n) {
;       const int cg = pn * 128 + wc * 32 + n * 16 + fr2;
;       w0[n] = ge.cw[cg]; w1[n] = ge.cw[DFF + cg]; w2[n] = ge.cw[2 * DFF + cg]; bs[n] = ge.cb[cg];
;     }
;     ...
;   u16* Cw = C + (size_t)(brow + wr * 64) * N + bcol + wc * 32;
; #pragma unroll
;   for (int ai = 0; ai < 2; ++ai)
; #pragma unroll
;     for (int bj = 0; bj < 2; ++bj)
; #pragma unroll
;       for (int m = 0; m < 4; ++m)
; #pragma unroll
;         for (int n = 0; n < 2; ++n)
; #pragma unroll
;           for (int j = 0; j < 4; ++j)
;             Cw[(size_t)(ai * 128 + m * 16 + fq2 * 4 + j) * N + (bj * 128 + n * 16 + fr2)] = f2bf(acc[ai][bj][m][n][j]);
.Lg_epi:
	v_readfirstlane_b32 s0, v160
	s_andn2_b32 s0, s0, 63
	s_andn2_b64 vcc, exec, s[2:3]
	v_or_b32_e32 v180, s0, v161
	s_nop 0
	v_bfe_u32 v181, v180, 4, 2
	v_and_b32_e32 v180, 15, v180
	s_cbranch_vccz .Lg_gate
	s_add_i32 s0, s51, s49
	s_mul_hi_u32 s1, s0, s44
	s_mul_i32 s0, s0, s44
	s_lshl_b64 s[0:1], s[0:1], 1
	s_add_u32 s0, s14, s0
	s_addc_u32 s1, s15, s1
	s_lshl_b64 s[4:5], s[92:93], 1
	s_add_u32 s0, s0, s4
	s_addc_u32 s1, s1, s5
	s_lshl_b32 s4, s50, 6
	s_add_u32 s0, s0, s4
	s_addc_u32 s1, s1, 0
	v_mul_u32_u24_e32 v153, s44, v180
	v_lshlrev_b32_e32 v153, 1, v153
	v_lshl_add_u32 v153, v181, 4, v153
	s_lshl_b32 s4, s44, 5
	s_lshl_b32 s5, s44, 7
	v_cvt_pk_bf16_f32 v184, v124, v125
	v_cvt_pk_bf16_f32 v185, v126, v127
	v_cvt_pk_bf16_f32 v186, v120, v121
	v_cvt_pk_bf16_f32 v187, v122, v123
	global_store_dwordx4 v153, v[184:187], s[0:1] sc1
	v_cvt_pk_bf16_f32 v188, v84, v85
	v_cvt_pk_bf16_f32 v189, v86, v87
	v_cvt_pk_bf16_f32 v190, v68, v69
	v_cvt_pk_bf16_f32 v191, v70, v71
	global_store_dwordx4 v153, v[188:191], s[0:1] offset:256 sc1
	s_add_u32 s0, s0, s4
	s_addc_u32 s1, s1, 0
	v_cvt_pk_bf16_f32 v192, v116, v117
	v_cvt_pk_bf16_f32 v193, v118, v119
	v_cvt_pk_bf16_f32 v194, v112, v113
	v_cvt_pk_bf16_f32 v195, v114, v115
	global_store_dwordx4 v153, v[192:195], s[0:1] sc1
	v_cvt_pk_bf16_f32 v196, v52, v53
	v_cvt_pk_bf16_f32 v197, v54, v55
	v_cvt_pk_bf16_f32 v198, v48, v49
	v_cvt_pk_bf16_f32 v199, v50, v51
	global_store_dwordx4 v153, v[196:199], s[0:1] offset:256 sc1
	s_add_u32 s0, s0, s4
	s_addc_u32 s1, s1, 0
	v_cvt_pk_bf16_f32 v184, v108, v109
	v_cvt_pk_bf16_f32 v185, v110, v111
	v_cvt_pk_bf16_f32 v186, v104, v105
	v_cvt_pk_bf16_f32 v187, v106, v107
	global_store_dwordx4 v153, v[184:187], s[0:1] sc1
	v_cvt_pk_bf16_f32 v188, v44, v45
	v_cvt_pk_bf16_f32 v189, v46, v47
	v_cvt_pk_bf16_f32 v190, v40, v41
	v_cvt_pk_bf16_f32 v191, v42, v43
	global_store_dwordx4 v153, v[188:191], s[0:1] offset:256 sc1
	s_add_u32 s0, s0, s4
	s_addc_u32 s1, s1, 0
	v_cvt_pk_bf16_f32 v192, v100, v101
	v_cvt_pk_bf16_f32 v193, v102, v103
	v_cvt_pk_bf16_f32 v194, v96, v97
	v_cvt_pk_bf16_f32 v195, v98, v99
	global_store_dwordx4 v153, v[192:195], s[0:1] sc1
	v_cvt_pk_bf16_f32 v196, v36, v37
	v_cvt_pk_bf16_f32 v197, v38, v39
	v_cvt_pk_bf16_f32 v198, v32, v33
	v_cvt_pk_bf16_f32 v199, v34, v35
	global_store_dwordx4 v153, v[196:199], s[0:1] offset:256 sc1
	s_add_u32 s0, s0, s4
	s_addc_u32 s1, s1, 0
	s_add_u32 s0, s0, s5
	s_addc_u32 s1, s1, 0
	v_cvt_pk_bf16_f32 v184, v28, v29
	v_cvt_pk_bf16_f32 v185, v30, v31
	v_cvt_pk_bf16_f32 v186, v24, v25
	v_cvt_pk_bf16_f32 v187, v26, v27
	global_store_dwordx4 v153, v[184:187], s[0:1] sc1
	v_cvt_pk_bf16_f32 v188, v56, v57
	v_cvt_pk_bf16_f32 v189, v58, v59
	v_cvt_pk_bf16_f32 v190, v60, v61
	v_cvt_pk_bf16_f32 v191, v62, v63
	global_store_dwordx4 v153, v[188:191], s[0:1] offset:256 sc1
	s_add_u32 s0, s0, s4
	s_addc_u32 s1, s1, 0
	v_cvt_pk_bf16_f32 v192, v20, v21
	v_cvt_pk_bf16_f32 v193, v22, v23
	v_cvt_pk_bf16_f32 v194, v16, v17
	v_cvt_pk_bf16_f32 v195, v18, v19
	global_store_dwordx4 v153, v[192:195], s[0:1] sc1
	v_cvt_pk_bf16_f32 v196, v64, v65
	v_cvt_pk_bf16_f32 v197, v66, v67
	v_cvt_pk_bf16_f32 v198, v72, v73
	v_cvt_pk_bf16_f32 v199, v74, v75
	global_store_dwordx4 v153, v[196:199], s[0:1] offset:256 sc1
	s_add_u32 s0, s0, s4
	s_addc_u32 s1, s1, 0
	v_cvt_pk_bf16_f32 v184, v12, v13
	v_cvt_pk_bf16_f32 v185, v14, v15
	v_cvt_pk_bf16_f32 v186, v8, v9
	v_cvt_pk_bf16_f32 v187, v10, v11
	global_store_dwordx4 v153, v[184:187], s[0:1] sc1
	v_cvt_pk_bf16_f32 v188, v76, v77
	v_cvt_pk_bf16_f32 v189, v78, v79
	v_cvt_pk_bf16_f32 v190, v80, v81
	v_cvt_pk_bf16_f32 v191, v82, v83
	global_store_dwordx4 v153, v[188:191], s[0:1] offset:256 sc1
	s_add_u32 s0, s0, s4
	s_addc_u32 s1, s1, 0
	v_cvt_pk_bf16_f32 v192, v4, v5
	v_cvt_pk_bf16_f32 v193, v6, v7
	v_cvt_pk_bf16_f32 v194, v0, v1
	v_cvt_pk_bf16_f32 v195, v2, v3
	global_store_dwordx4 v153, v[192:195], s[0:1] sc1
	v_cvt_pk_bf16_f32 v196, v88, v89
	v_cvt_pk_bf16_f32 v197, v90, v91
	v_cvt_pk_bf16_f32 v198, v92, v93
	v_cvt_pk_bf16_f32 v199, v94, v95
	global_store_dwordx4 v153, v[196:199], s[0:1] offset:256 sc1
	s_branch .Lg_post
.Lg_gate:
	s_add_i32 s62, s1, 0x21000
	v_lshlrev_b32_e32 v154, 5, v181
	v_add_u32_e32 v154, s62, v154
	ds_read_b128 v[184:187], v154 offset:0
	ds_read_b128 v[188:191], v154 offset:16
	ds_read_b128 v[192:195], v154 offset:128
	ds_read_b128 v[196:199], v154 offset:144
	ds_read_b128 v[200:203], v154 offset:256
	ds_read_b128 v[204:207], v154 offset:272
	ds_read_b128 v[208:211], v154 offset:384
	ds_read_b128 v[212:215], v154 offset:400
	s_lshl_b32 s0, s47, 5
	s_and_b32 s0, s0, 0xffffff00
	s_lshl_b32 s1, s50, 6
	s_add_i32 s28, s0, s1
	s_add_i32 s0, s51, s49
	s_mul_hi_u32 s1, s0, s85
	s_mul_i32 s0, s0, s85
	s_add_u32 s0, s0, s28
	s_addc_u32 s1, s1, 0
	s_add_u32 s0, s80, s0
	s_addc_u32 s1, s81, s1
	s_ashr_i32 s4, s49, 8
	s_mul_i32 s4, s4, 0x5800
	s_add_i32 s4, s4, s28
	s_add_u32 s6, s22, s4
	s_addc_u32 s7, s23, 0
	s_add_u32 s54, s82, s4
	s_addc_u32 s55, s83, 0
	s_sub_u32 s54, s54, 0x26800
	s_subb_u32 s55, s55, 0
	s_add_u32 s4, s20, s4
	s_addc_u32 s5, s21, 0
	v_mul_u32_u24_e32 v153, 0x2c00, v180
	v_lshl_add_u32 v153, v181, 4, v153
	v_and_b32_e32 v157, 1, v180
	v_lshlrev_b32_e32 v157, 5, v157
	v_lshl_add_u32 v157, v181, 6, v157
	s_lshl_b32 s62, s50, 8
	s_add_i32 s62, s62, 0x20000
	v_add_u32_e32 v157, s62, v157
	s_lshl_b32 s62, s34, 10
	v_add_u32_e32 v158, s62, v157
	s_add_i32 s62, s34, 3
	s_and_b32 s62, s62, 3
	s_lshl_b32 s62, s62, 10
	v_add_u32_e32 v159, s62, v157
	s_mov_b32 s52, 0xbdd2d3e8
	s_mov_b32 s53, 0xbdd2d3e8
	s_mov_b32 s94, 1.0
	s_mov_b32 s95, 1.0
	s_mov_b32 exec_lo, 0xc000c000
	s_mov_b32 exec_hi, 0xc000c000
	ds_write_b128 v158, v[100:103]
	ds_write_b128 v158, v[96:99] offset:16
	ds_write_b128 v158, v[4:7] offset:2048
	ds_write_b128 v158, v[0:3] offset:2064
	s_mov_b64 exec, -1
	s_waitcnt lgkmcnt(0)
	s_barrier
; DEV float bf2f(u16 h) { return __uint_as_float(((uint32_t)h) << 16); }
; DEV float gelu_tanh(float x) {
;   const float e = __builtin_amdgcn_exp2f(x * __builtin_fmaf(x * x, -0.10294324f, -2.3022082f));
;   return x * __builtin_amdgcn_rcpf(1.0f + e);
; }
; DEV void gemm_tile(const u16* __restrict__ A, const u16* __restrict__ Bt, u16* __restrict__ C, int N, int K,
;                    int brow, int bcol, unsigned char* smem, int epi, const GateEpi& ge) {
;     ...
;         const int R0 = ai * 128 + wr * 64 + m * 16 + fq2 * 4;
; #pragma unroll
;         for (int n = 0; n < 2; ++n) {
;           const int cl = wc * 32 + n * 16 + fr2, cg = pn * 128 + cl;
;           float am2 = 0.f, am1 = 0.f;
;           if (R0 > 0) { am2 = bf2f(sAt[(R0 - 2) * AS + cl]); am1 = bf2f(sAt[(R0 - 1) * AS + cl]); }
; #pragma unroll
;           for (int j = 0; j < 4; ++j) {
;             const float a0 = acc[ai][0][m][n][j], b0 = acc[ai][1][m][n][j];
;             if (R0 > 0 || j >= 2) {
;               const float gv = gelu_tanh(bs[n] + w0[n] * am2 + w1[n] * am1 + w2[n] * a0) * b0;
;               ge.g[(size_t)(brow + R0 + j) * DFF + cg] = f2bf(gv);
;             } else {
;               ge.first_a[((size_t)pm * 2 + j) * DFF + cg] = sAt[(R0 + j) * AS + cl];
;               ge.first_b[((size_t)pm * 2 + j) * DFF + cg] = f2bf(b0);
;             }
;             if (R0 == 252 && j >= 2) ge.halo_a[((size_t)pm * 2 + (j - 2)) * DFF + cg] = sAt[(R0 + j) * AS + cl];
;             am2 = am1; am1 = a0;
	ds_read_b128 v[232:235], v159
	ds_read_b128 v[236:239], v159 offset:16
	s_add_i32 s62, s34, 1
	s_lshl_b32 s62, s62, 10
	v_add_u32_e32 v156, s62, v157
	v_cmp_eq_u32_e32 vcc, 0, v180
	s_nop 1
	v_cndmask_b32_e32 v216, 0, v192, vcc
	v_cndmask_b32_e32 v217, 0, v193, vcc
	v_cndmask_b32_e32 v218, 0, v194, vcc
	v_cndmask_b32_e32 v219, 0, v195, vcc
	v_cndmask_b32_e32 v220, 0, v196, vcc
	v_cndmask_b32_e32 v221, 0, v197, vcc
	v_cndmask_b32_e32 v222, 0, v198, vcc
	v_cndmask_b32_e32 v223, 0, v199, vcc
	v_cmp_gt_u32_e32 vcc, 2, v180
	s_nop 1
	v_cndmask_b32_e32 v224, 0, v184, vcc
	v_cndmask_b32_e32 v225, 0, v185, vcc
	v_cndmask_b32_e32 v226, 0, v186, vcc
	v_cndmask_b32_e32 v227, 0, v187, vcc
	v_cndmask_b32_e32 v228, 0, v188, vcc
	v_cndmask_b32_e32 v229, 0, v189, vcc
	v_cndmask_b32_e32 v230, 0, v190, vcc
	v_cndmask_b32_e32 v231, 0, v191, vcc
	v_mov_b32_e32 v180, v163
	v_mov_b32_e32 v181, v163
	s_waitcnt lgkmcnt(0)
	v_pk_fma_f32 v[240:241], v[200:201], v[124:125], v[208:209]
	v_pk_fma_f32 v[242:243], v[202:203], v[126:127], v[210:211]
	v_pk_fma_f32 v[244:245], v[204:205], v[120:121], v[212:213]
	v_pk_fma_f32 v[246:247], v[206:207], v[122:123], v[214:215]
	v_fmac_f32_dpp v240, v124, v192 row_shr:1 row_mask:0xf bank_mask:0xf
	v_fmac_f32_dpp v241, v125, v193 row_shr:1 row_mask:0xf bank_mask:0xf
	v_fmac_f32_dpp v242, v126, v194 row_shr:1 row_mask:0xf bank_mask:0xf
	v_fmac_f32_dpp v243, v127, v195 row_shr:1 row_mask:0xf bank_mask:0xf
	v_fmac_f32_dpp v244, v120, v196 row_shr:1 row_mask:0xf bank_mask:0xf
	v_fmac_f32_dpp v245, v121, v197 row_shr:1 row_mask:0xf bank_mask:0xf
	v_fmac_f32_dpp v246, v122, v198 row_shr:1 row_mask:0xf bank_mask:0xf
	v_fmac_f32_dpp v247, v123, v199 row_shr:1 row_mask:0xf bank_mask:0xf
	v_fmac_f32_dpp v240, v232, v216 row_ror:1 row_mask:0xf bank_mask:0xf
	v_fmac_f32_dpp v241, v233, v217 row_ror:1 row_mask:0xf bank_mask:0xf
	v_fmac_f32_dpp v242, v234, v218 row_ror:1 row_mask:0xf bank_mask:0xf
	v_fmac_f32_dpp v243, v235, v219 row_ror:1 row_mask:0xf bank_mask:0xf
	v_fmac_f32_dpp v244, v236, v220 row_ror:1 row_mask:0xf bank_mask:0xf
	v_fmac_f32_dpp v245, v237, v221 row_ror:1 row_mask:0xf bank_mask:0xf
	v_fmac_f32_dpp v246, v238, v222 row_ror:1 row_mask:0xf bank_mask:0xf
	v_fmac_f32_dpp v247, v239, v223 row_ror:1 row_mask:0xf bank_mask:0xf
	v_fmac_f32_dpp v240, v124, v184 row_shr:2 row_mask:0xf bank_mask:0xf
	v_fmac_f32_dpp v241, v125, v185 row_shr:2 row_mask:0xf bank_mask:0xf
	v_fmac_f32_dpp v242, v126, v186 row_shr:2 row_mask:0xf bank_mask:0xf
	v_fmac_f32_dpp v243, v127, v187 row_shr:2 row_mask:0xf bank_mask:0xf
	v_fmac_f32_dpp v244, v120, v188 row_shr:2 row_mask:0xf bank_mask:0xf
	v_fmac_f32_dpp v245, v121, v189 row_shr:2 row_mask:0xf bank_mask:0xf
	v_fmac_f32_dpp v246, v122, v190 row_shr:2 row_mask:0xf bank_mask:0xf
	v_fmac_f32_dpp v247, v123, v191 row_shr:2 row_mask:0xf bank_mask:0xf
	v_fmac_f32_dpp v240, v232, v224 row_ror:2 row_mask:0xf bank_mask:0xf
	v_fmac_f32_dpp v241, v233, v225 row_ror:2 row_mask:0xf bank_mask:0xf
	v_fmac_f32_dpp v242, v234, v226 row_ror:2 row_mask:0xf bank_mask:0xf
	v_fmac_f32_dpp v243, v235, v227 row_ror:2 row_mask:0xf bank_mask:0xf
	v_fmac_f32_dpp v244, v236, v228 row_ror:2 row_mask:0xf bank_mask:0xf
	v_fmac_f32_dpp v245, v237, v229 row_ror:2 row_mask:0xf bank_mask:0xf
	v_fmac_f32_dpp v246, v238, v230 row_ror:2 row_mask:0xf bank_mask:0xf
	v_fmac_f32_dpp v247, v239, v231 row_ror:2 row_mask:0xf bank_mask:0xf
	ds_read_b128 v[232:235], v156
	ds_read_b128 v[236:239], v156 offset:16
	v_pk_mul_f32 v[248:249], v[240:241], v[240:241]
	v_pk_mul_f32 v[250:251], v[242:243], v[242:243]
	v_pk_mul_f32 v[182:183], v[244:245], v[244:245]
	v_pk_mul_f32 v[154:155], v[246:247], v[246:247]
	v_pk_fma_f32 v[248:249], v[248:249], s[52:53], v[180:181]
	v_pk_fma_f32 v[250:251], v[250:251], s[52:53], v[180:181]
	v_pk_fma_f32 v[182:183], v[182:183], s[52:53], v[180:181]
	v_pk_fma_f32 v[154:155], v[154:155], s[52:53], v[180:181]
	v_pk_mul_f32 v[248:249], v[240:241], v[248:249]
	v_pk_mul_f32 v[250:251], v[242:243], v[250:251]
	v_pk_mul_f32 v[182:183], v[244:245], v[182:183]
	v_pk_mul_f32 v[154:155], v[246:247], v[154:155]
	v_exp_f32_e32 v248, v248
	v_exp_f32_e32 v249, v249
	v_exp_f32_e32 v250, v250
	v_exp_f32_e32 v251, v251
	v_exp_f32_e32 v182, v182
	v_exp_f32_e32 v183, v183
	v_exp_f32_e32 v154, v154
	v_exp_f32_e32 v155, v155
	v_pk_add_f32 v[248:249], v[248:249], s[94:95]
	v_pk_add_f32 v[250:251], v[250:251], s[94:95]
	v_pk_add_f32 v[182:183], v[182:183], s[94:95]
	v_pk_add_f32 v[154:155], v[154:155], s[94:95]
	v_rcp_f32_e32 v248, v248
	v_rcp_f32_e32 v249, v249
	v_rcp_f32_e32 v250, v250
	v_rcp_f32_e32 v251, v251
	v_rcp_f32_e32 v182, v182
	v_rcp_f32_e32 v183, v183
	v_rcp_f32_e32 v154, v154
	v_rcp_f32_e32 v155, v155
	v_pk_mul_f32 v[240:241], v[240:241], v[248:249]
	v_pk_mul_f32 v[242:243], v[242:243], v[250:251]
	v_pk_mul_f32 v[244:245], v[244:245], v[182:183]
	v_pk_mul_f32 v[246:247], v[246:247], v[154:155]
	v_pk_mul_f32 v[240:241], v[240:241], v[84:85]
	v_pk_mul_f32 v[242:243], v[242:243], v[86:87]
	v_pk_mul_f32 v[244:245], v[244:245], v[68:69]
	v_pk_mul_f32 v[246:247], v[246:247], v[70:71]
	v_cvt_pk_bf16_f32 v248, v240, v241
	v_cvt_pk_bf16_f32 v249, v242, v243
	v_cvt_pk_bf16_f32 v250, v244, v245
	v_cvt_pk_bf16_f32 v251, v246, v247
	s_cmp_lg_u32 s34, 0
	s_cbranch_scc1 .Lgate_plain00_0
	s_mov_b32 exec_lo, 0x30003
	s_mov_b32 exec_hi, 0x30003
	v_cvt_pk_bf16_f32 v240, v124, v125
	v_cvt_pk_bf16_f32 v241, v126, v127
	v_cvt_pk_bf16_f32 v242, v120, v121
	v_cvt_pk_bf16_f32 v243, v122, v123
	v_cvt_pk_bf16_f32 v244, v84, v85
	v_cvt_pk_bf16_f32 v245, v86, v87
	v_cvt_pk_bf16_f32 v246, v68, v69
	v_cvt_pk_bf16_f32 v247, v70, v71
	global_store_dwordx4 v153, v[240:243], s[4:5] sc1
	global_store_dwordx4 v153, v[244:247], s[6:7] sc1
	s_not_b64 exec, exec
	global_store_dwordx4 v153, v[248:251], s[0:1] sc1
	s_mov_b64 exec, -1
	s_branch .Lgate_done00_0
; DEV float bf2f(u16 h) { return __uint_as_float(((uint32_t)h) << 16); }
; DEV float gelu_tanh(float x) {
;   const float e = __builtin_amdgcn_exp2f(x * __builtin_fmaf(x * x, -0.10294324f, -2.3022082f));
;   return x * __builtin_amdgcn_rcpf(1.0f + e);
; }
; DEV void gemm_tile(const u16* __restrict__ A, const u16* __restrict__ Bt, u16* __restrict__ C, int N, int K,
;                    int brow, int bcol, unsigned char* smem, int epi, const GateEpi& ge) {
;     ...
;         const int R0 = ai * 128 + wr * 64 + m * 16 + fq2 * 4;
; #pragma unroll
;         for (int n = 0; n < 2; ++n) {
;           const int cl = wc * 32 + n * 16 + fr2, cg = pn * 128 + cl;
;           float am2 = 0.f, am1 = 0.f;
;           if (R0 > 0) { am2 = bf2f(sAt[(R0 - 2) * AS + cl]); am1 = bf2f(sAt[(R0 - 1) * AS + cl]); }
; #pragma unroll
;           for (int j = 0; j < 4; ++j) {
;             const float a0 = acc[ai][0][m][n][j], b0 = acc[ai][1][m][n][j];
;             if (R0 > 0 || j >= 2) {
;               const float gv = gelu_tanh(bs[n] + w0[n] * am2 + w1[n] * am1 + w2[n] * a0) * b0;
;               ge.g[(size_t)(brow + R0 + j) * DFF + cg] = f2bf(gv);
;             } else {
;               ge.first_a[((size_t)pm * 2 + j) * DFF + cg] = sAt[(R0 + j) * AS + cl];
;               ge.first_b[((size_t)pm * 2 + j) * DFF + cg] = f2bf(b0);
;             }
;             if (R0 == 252 && j >= 2) ge.halo_a[((size_t)pm * 2 + (j - 2)) * DFF + cg] = sAt[(R0 + j) * AS + cl];
;             am2 = am1; am1 = a0;
.Lgate_plain00_0:
	global_store_dwordx4 v153, v[248:251], s[0:1] sc1
.Lgate_done00_0:
	s_add_u32 s0, s0, 0x2c000
	s_addc_u32 s1, s1, 0
	v_pk_fma_f32 v[240:241], v[200:201], v[116:117], v[208:209]
	v_pk_fma_f32 v[242:243], v[202:203], v[118:119], v[210:211]
	v_pk_fma_f32 v[244:245], v[204:205], v[112:113], v[212:213]
	v_pk_fma_f32 v[246:247], v[206:207], v[114:115], v[214:215]
	v_fmac_f32_dpp v240, v116, v192 row_shr:1 row_mask:0xf bank_mask:0xf
	v_fmac_f32_dpp v241, v117, v193 row_shr:1 row_mask:0xf bank_mask:0xf
	v_fmac_f32_dpp v242, v118, v194 row_shr:1 row_mask:0xf bank_mask:0xf
	v_fmac_f32_dpp v243, v119, v195 row_shr:1 row_mask:0xf bank_mask:0xf
	v_fmac_f32_dpp v244, v112, v196 row_shr:1 row_mask:0xf bank_mask:0xf
	v_fmac_f32_dpp v245, v113, v197 row_shr:1 row_mask:0xf bank_mask:0xf
	v_fmac_f32_dpp v246, v114, v198 row_shr:1 row_mask:0xf bank_mask:0xf
	v_fmac_f32_dpp v247, v115, v199 row_shr:1 row_mask:0xf bank_mask:0xf
	v_fmac_f32_dpp v240, v124, v216 row_ror:1 row_mask:0xf bank_mask:0xf
	v_fmac_f32_dpp v241, v125, v217 row_ror:1 row_mask:0xf bank_mask:0xf
	v_fmac_f32_dpp v242, v126, v218 row_ror:1 row_mask:0xf bank_mask:0xf
	v_fmac_f32_dpp v243, v127, v219 row_ror:1 row_mask:0xf bank_mask:0xf
	v_fmac_f32_dpp v244, v120, v220 row_ror:1 row_mask:0xf bank_mask:0xf
	v_fmac_f32_dpp v245, v121, v221 row_ror:1 row_mask:0xf bank_mask:0xf
	v_fmac_f32_dpp v246, v122, v222 row_ror:1 row_mask:0xf bank_mask:0xf
	v_fmac_f32_dpp v247, v123, v223 row_ror:1 row_mask:0xf bank_mask:0xf
	v_fmac_f32_dpp v240, v116, v184 row_shr:2 row_mask:0xf bank_mask:0xf
	v_fmac_f32_dpp v241, v117, v185 row_shr:2 row_mask:0xf bank_mask:0xf
	v_fmac_f32_dpp v242, v118, v186 row_shr:2 row_mask:0xf bank_mask:0xf
	v_fmac_f32_dpp v243, v119, v187 row_shr:2 row_mask:0xf bank_mask:0xf
	v_fmac_f32_dpp v244, v112, v188 row_shr:2 row_mask:0xf bank_mask:0xf
	v_fmac_f32_dpp v245, v113, v189 row_shr:2 row_mask:0xf bank_mask:0xf
	v_fmac_f32_dpp v246, v114, v190 row_shr:2 row_mask:0xf bank_mask:0xf
	v_fmac_f32_dpp v247, v115, v191 row_shr:2 row_mask:0xf bank_mask:0xf
	v_fmac_f32_dpp v240, v124, v224 row_ror:2 row_mask:0xf bank_mask:0xf
	v_fmac_f32_dpp v241, v125, v225 row_ror:2 row_mask:0xf bank_mask:0xf
	v_fmac_f32_dpp v242, v126, v226 row_ror:2 row_mask:0xf bank_mask:0xf
	v_fmac_f32_dpp v243, v127, v227 row_ror:2 row_mask:0xf bank_mask:0xf
	v_fmac_f32_dpp v244, v120, v228 row_ror:2 row_mask:0xf bank_mask:0xf
	v_fmac_f32_dpp v245, v121, v229 row_ror:2 row_mask:0xf bank_mask:0xf
	v_fmac_f32_dpp v246, v122, v230 row_ror:2 row_mask:0xf bank_mask:0xf
	v_fmac_f32_dpp v247, v123, v231 row_ror:2 row_mask:0xf bank_mask:0xf
	v_pk_mul_f32 v[248:249], v[240:241], v[240:241]
	v_pk_mul_f32 v[250:251], v[242:243], v[242:243]
	v_pk_mul_f32 v[182:183], v[244:245], v[244:245]
	v_pk_mul_f32 v[154:155], v[246:247], v[246:247]
	v_pk_fma_f32 v[248:249], v[248:249], s[52:53], v[180:181]
	v_pk_fma_f32 v[250:251], v[250:251], s[52:53], v[180:181]
	v_pk_fma_f32 v[182:183], v[182:183], s[52:53], v[180:181]
	v_pk_fma_f32 v[154:155], v[154:155], s[52:53], v[180:181]
	v_pk_mul_f32 v[248:249], v[240:241], v[248:249]
	v_pk_mul_f32 v[250:251], v[242:243], v[250:251]
	v_pk_mul_f32 v[182:183], v[244:245], v[182:183]
	v_pk_mul_f32 v[154:155], v[246:247], v[154:155]
	v_exp_f32_e32 v248, v248
	v_exp_f32_e32 v249, v249
	v_exp_f32_e32 v250, v250
	v_exp_f32_e32 v251, v251
	v_exp_f32_e32 v182, v182
	v_exp_f32_e32 v183, v183
	v_exp_f32_e32 v154, v154
	v_exp_f32_e32 v155, v155
	v_pk_add_f32 v[248:249], v[248:249], s[94:95]
	v_pk_add_f32 v[250:251], v[250:251], s[94:95]
	v_pk_add_f32 v[182:183], v[182:183], s[94:95]
	v_pk_add_f32 v[154:155], v[154:155], s[94:95]
	v_rcp_f32_e32 v248, v248
	v_rcp_f32_e32 v249, v249
	v_rcp_f32_e32 v250, v250
	v_rcp_f32_e32 v251, v251
	v_rcp_f32_e32 v182, v182
	v_rcp_f32_e32 v183, v183
	v_rcp_f32_e32 v154, v154
	v_rcp_f32_e32 v155, v155
	v_pk_mul_f32 v[240:241], v[240:241], v[248:249]
	v_pk_mul_f32 v[242:243], v[242:243], v[250:251]
	v_pk_mul_f32 v[244:245], v[244:245], v[182:183]
	v_pk_mul_f32 v[246:247], v[246:247], v[154:155]
	v_pk_mul_f32 v[240:241], v[240:241], v[52:53]
	v_pk_mul_f32 v[242:243], v[242:243], v[54:55]
	v_pk_mul_f32 v[244:245], v[244:245], v[48:49]
	v_pk_mul_f32 v[246:247], v[246:247], v[50:51]
	v_cvt_pk_bf16_f32 v248, v240, v241
	v_cvt_pk_bf16_f32 v249, v242, v243
	v_cvt_pk_bf16_f32 v250, v244, v245
	v_cvt_pk_bf16_f32 v251, v246, v247
	global_store_dwordx4 v153, v[248:251], s[0:1] sc1
	s_add_u32 s0, s0, 0x2c000
	s_addc_u32 s1, s1, 0
	v_pk_fma_f32 v[240:241], v[200:201], v[108:109], v[208:209]
	v_pk_fma_f32 v[242:243], v[202:203], v[110:111], v[210:211]
	v_pk_fma_f32 v[244:245], v[204:205], v[104:105], v[212:213]
	v_pk_fma_f32 v[246:247], v[206:207], v[106:107], v[214:215]
	v_fmac_f32_dpp v240, v108, v192 row_shr:1 row_mask:0xf bank_mask:0xf
	v_fmac_f32_dpp v241, v109, v193 row_shr:1 row_mask:0xf bank_mask:0xf
	v_fmac_f32_dpp v242, v110, v194 row_shr:1 row_mask:0xf bank_mask:0xf
	v_fmac_f32_dpp v243, v111, v195 row_shr:1 row_mask:0xf bank_mask:0xf
	v_fmac_f32_dpp v244, v104, v196 row_shr:1 row_mask:0xf bank_mask:0xf
	v_fmac_f32_dpp v245, v105, v197 row_shr:1 row_mask:0xf bank_mask:0xf
	v_fmac_f32_dpp v246, v106, v198 row_shr:1 row_mask:0xf bank_mask:0xf
	v_fmac_f32_dpp v247, v107, v199 row_shr:1 row_mask:0xf bank_mask:0xf
	v_fmac_f32_dpp v240, v116, v216 row_ror:1 row_mask:0xf bank_mask:0xf
	v_fmac_f32_dpp v241, v117, v217 row_ror:1 row_mask:0xf bank_mask:0xf
	v_fmac_f32_dpp v242, v118, v218 row_ror:1 row_mask:0xf bank_mask:0xf
	v_fmac_f32_dpp v243, v119, v219 row_ror:1 row_mask:0xf bank_mask:0xf
	v_fmac_f32_dpp v244, v112, v220 row_ror:1 row_mask:0xf bank_mask:0xf
; DEV float bf2f(u16 h) { return __uint_as_float(((uint32_t)h) << 16); }
; DEV float gelu_tanh(float x) {
;   const float e = __builtin_amdgcn_exp2f(x * __builtin_fmaf(x * x, -0.10294324f, -2.3022082f));
;   return x * __builtin_amdgcn_rcpf(1.0f + e);
; }
; DEV void gemm_tile(const u16* __restrict__ A, const u16* __restrict__ Bt, u16* __restrict__ C, int N, int K,
;                    int brow, int bcol, unsigned char* smem, int epi, const GateEpi& ge) {
;     ...
;         const int R0 = ai * 128 + wr * 64 + m * 16 + fq2 * 4;
; #pragma unroll
;         for (int n = 0; n < 2; ++n) {
;           const int cl = wc * 32 + n * 16 + fr2, cg = pn * 128 + cl;
;           float am2 = 0.f, am1 = 0.f;
;           if (R0 > 0) { am2 = bf2f(sAt[(R0 - 2) * AS + cl]); am1 = bf2f(sAt[(R0 - 1) * AS + cl]); }
; #pragma unroll
;           for (int j = 0; j < 4; ++j) {
;             const float a0 = acc[ai][0][m][n][j], b0 = acc[ai][1][m][n][j];
;             if (R0 > 0 || j >= 2) {
;               const float gv = gelu_tanh(bs[n] + w0[n] * am2 + w1[n] * am1 + w2[n] * a0) * b0;
;               ge.g[(size_t)(brow + R0 + j) * DFF + cg] = f2bf(gv);
;             } else {
;               ge.first_a[((size_t)pm * 2 + j) * DFF + cg] = sAt[(R0 + j) * AS + cl];
;               ge.first_b[((size_t)pm * 2 + j) * DFF + cg] = f2bf(b0);
;             }
;             if (R0 == 252 && j >= 2) ge.halo_a[((size_t)pm * 2 + (j - 2)) * DFF + cg] = sAt[(R0 + j) * AS + cl];
;             am2 = am1; am1 = a0;
	v_fmac_f32_dpp v245, v113, v221 row_ror:1 row_mask:0xf bank_mask:0xf
	v_fmac_f32_dpp v246, v114, v222 row_ror:1 row_mask:0xf bank_mask:0xf
	v_fmac_f32_dpp v247, v115, v223 row_ror:1 row_mask:0xf bank_mask:0xf
	v_fmac_f32_dpp v240, v108, v184 row_shr:2 row_mask:0xf bank_mask:0xf
	v_fmac_f32_dpp v241, v109, v185 row_shr:2 row_mask:0xf bank_mask:0xf
	v_fmac_f32_dpp v242, v110, v186 row_shr:2 row_mask:0xf bank_mask:0xf
	v_fmac_f32_dpp v243, v111, v187 row_shr:2 row_mask:0xf bank_mask:0xf
	v_fmac_f32_dpp v244, v104, v188 row_shr:2 row_mask:0xf bank_mask:0xf
	v_fmac_f32_dpp v245, v105, v189 row_shr:2 row_mask:0xf bank_mask:0xf
	v_fmac_f32_dpp v246, v106, v190 row_shr:2 row_mask:0xf bank_mask:0xf
	v_fmac_f32_dpp v247, v107, v191 row_shr:2 row_mask:0xf bank_mask:0xf
	v_fmac_f32_dpp v240, v116, v224 row_ror:2 row_mask:0xf bank_mask:0xf
	v_fmac_f32_dpp v241, v117, v225 row_ror:2 row_mask:0xf bank_mask:0xf
	v_fmac_f32_dpp v242, v118, v226 row_ror:2 row_mask:0xf bank_mask:0xf
	v_fmac_f32_dpp v243, v119, v227 row_ror:2 row_mask:0xf bank_mask:0xf
	v_fmac_f32_dpp v244, v112, v228 row_ror:2 row_mask:0xf bank_mask:0xf
	v_fmac_f32_dpp v245, v113, v229 row_ror:2 row_mask:0xf bank_mask:0xf
	v_fmac_f32_dpp v246, v114, v230 row_ror:2 row_mask:0xf bank_mask:0xf
	v_fmac_f32_dpp v247, v115, v231 row_ror:2 row_mask:0xf bank_mask:0xf
	v_pk_mul_f32 v[248:249], v[240:241], v[240:241]
	v_pk_mul_f32 v[250:251], v[242:243], v[242:243]
	v_pk_mul_f32 v[182:183], v[244:245], v[244:245]
	v_pk_mul_f32 v[154:155], v[246:247], v[246:247]
	v_pk_fma_f32 v[248:249], v[248:249], s[52:53], v[180:181]
	v_pk_fma_f32 v[250:251], v[250:251], s[52:53], v[180:181]
	v_pk_fma_f32 v[182:183], v[182:183], s[52:53], v[180:181]
	v_pk_fma_f32 v[154:155], v[154:155], s[52:53], v[180:181]
	v_pk_mul_f32 v[248:249], v[240:241], v[248:249]
	v_pk_mul_f32 v[250:251], v[242:243], v[250:251]
	v_pk_mul_f32 v[182:183], v[244:245], v[182:183]
	v_pk_mul_f32 v[154:155], v[246:247], v[154:155]
	v_exp_f32_e32 v248, v248
	v_exp_f32_e32 v249, v249
	v_exp_f32_e32 v250, v250
	v_exp_f32_e32 v251, v251
	v_exp_f32_e32 v182, v182
	v_exp_f32_e32 v183, v183
	v_exp_f32_e32 v154, v154
	v_exp_f32_e32 v155, v155
	v_pk_add_f32 v[248:249], v[248:249], s[94:95]
	v_pk_add_f32 v[250:251], v[250:251], s[94:95]
	v_pk_add_f32 v[182:183], v[182:183], s[94:95]
	v_pk_add_f32 v[154:155], v[154:155], s[94:95]
	v_rcp_f32_e32 v248, v248
	v_rcp_f32_e32 v249, v249
	v_rcp_f32_e32 v250, v250
	v_rcp_f32_e32 v251, v251
	v_rcp_f32_e32 v182, v182
	v_rcp_f32_e32 v183, v183
	v_rcp_f32_e32 v154, v154
	v_rcp_f32_e32 v155, v155
	v_pk_mul_f32 v[240:241], v[240:241], v[248:249]
	v_pk_mul_f32 v[242:243], v[242:243], v[250:251]
	v_pk_mul_f32 v[244:245], v[244:245], v[182:183]
	v_pk_mul_f32 v[246:247], v[246:247], v[154:155]
	v_pk_mul_f32 v[240:241], v[240:241], v[44:45]
	v_pk_mul_f32 v[242:243], v[242:243], v[46:47]
	v_pk_mul_f32 v[244:245], v[244:245], v[40:41]
	v_pk_mul_f32 v[246:247], v[246:247], v[42:43]
	v_cvt_pk_bf16_f32 v248, v240, v241
	v_cvt_pk_bf16_f32 v249, v242, v243
	v_cvt_pk_bf16_f32 v250, v244, v245
	v_cvt_pk_bf16_f32 v251, v246, v247
	global_store_dwordx4 v153, v[248:251], s[0:1] sc1
	s_add_u32 s0, s0, 0x2c000
	s_addc_u32 s1, s1, 0
	v_pk_fma_f32 v[240:241], v[200:201], v[100:101], v[208:209]
	v_pk_fma_f32 v[242:243], v[202:203], v[102:103], v[210:211]
	v_pk_fma_f32 v[244:245], v[204:205], v[96:97], v[212:213]
	v_pk_fma_f32 v[246:247], v[206:207], v[98:99], v[214:215]
	v_fmac_f32_dpp v240, v100, v192 row_shr:1 row_mask:0xf bank_mask:0xf
	v_fmac_f32_dpp v241, v101, v193 row_shr:1 row_mask:0xf bank_mask:0xf
	v_fmac_f32_dpp v242, v102, v194 row_shr:1 row_mask:0xf bank_mask:0xf
	v_fmac_f32_dpp v243, v103, v195 row_shr:1 row_mask:0xf bank_mask:0xf
	v_fmac_f32_dpp v244, v96, v196 row_shr:1 row_mask:0xf bank_mask:0xf
	v_fmac_f32_dpp v245, v97, v197 row_shr:1 row_mask:0xf bank_mask:0xf
	v_fmac_f32_dpp v246, v98, v198 row_shr:1 row_mask:0xf bank_mask:0xf
	v_fmac_f32_dpp v247, v99, v199 row_shr:1 row_mask:0xf bank_mask:0xf
	v_fmac_f32_dpp v240, v108, v216 row_ror:1 row_mask:0xf bank_mask:0xf
	v_fmac_f32_dpp v241, v109, v217 row_ror:1 row_mask:0xf bank_mask:0xf
	v_fmac_f32_dpp v242, v110, v218 row_ror:1 row_mask:0xf bank_mask:0xf
	v_fmac_f32_dpp v243, v111, v219 row_ror:1 row_mask:0xf bank_mask:0xf
	v_fmac_f32_dpp v244, v104, v220 row_ror:1 row_mask:0xf bank_mask:0xf
	v_fmac_f32_dpp v245, v105, v221 row_ror:1 row_mask:0xf bank_mask:0xf
	v_fmac_f32_dpp v246, v106, v222 row_ror:1 row_mask:0xf bank_mask:0xf
	v_fmac_f32_dpp v247, v107, v223 row_ror:1 row_mask:0xf bank_mask:0xf
	v_fmac_f32_dpp v240, v100, v184 row_shr:2 row_mask:0xf bank_mask:0xf
	v_fmac_f32_dpp v241, v101, v185 row_shr:2 row_mask:0xf bank_mask:0xf
	v_fmac_f32_dpp v242, v102, v186 row_shr:2 row_mask:0xf bank_mask:0xf
	v_fmac_f32_dpp v243, v103, v187 row_shr:2 row_mask:0xf bank_mask:0xf
	v_fmac_f32_dpp v244, v96, v188 row_shr:2 row_mask:0xf bank_mask:0xf
	v_fmac_f32_dpp v245, v97, v189 row_shr:2 row_mask:0xf bank_mask:0xf
	v_fmac_f32_dpp v246, v98, v190 row_shr:2 row_mask:0xf bank_mask:0xf
	v_fmac_f32_dpp v247, v99, v191 row_shr:2 row_mask:0xf bank_mask:0xf
	v_fmac_f32_dpp v240, v108, v224 row_ror:2 row_mask:0xf bank_mask:0xf
	v_fmac_f32_dpp v241, v109, v225 row_ror:2 row_mask:0xf bank_mask:0xf
	v_fmac_f32_dpp v242, v110, v226 row_ror:2 row_mask:0xf bank_mask:0xf
	v_fmac_f32_dpp v243, v111, v227 row_ror:2 row_mask:0xf bank_mask:0xf
	v_fmac_f32_dpp v244, v104, v228 row_ror:2 row_mask:0xf bank_mask:0xf
	v_fmac_f32_dpp v245, v105, v229 row_ror:2 row_mask:0xf bank_mask:0xf
	v_fmac_f32_dpp v246, v106, v230 row_ror:2 row_mask:0xf bank_mask:0xf
	v_fmac_f32_dpp v247, v107, v231 row_ror:2 row_mask:0xf bank_mask:0xf
; DEV float bf2f(u16 h) { return __uint_as_float(((uint32_t)h) << 16); }
; DEV float gelu_tanh(float x) {
;   const float e = __builtin_amdgcn_exp2f(x * __builtin_fmaf(x * x, -0.10294324f, -2.3022082f));
;   return x * __builtin_amdgcn_rcpf(1.0f + e);
; }
; DEV void gemm_tile(const u16* __restrict__ A, const u16* __restrict__ Bt, u16* __restrict__ C, int N, int K,
;                    int brow, int bcol, unsigned char* smem, int epi, const GateEpi& ge) {
;     ...
;         const int R0 = ai * 128 + wr * 64 + m * 16 + fq2 * 4;
; #pragma unroll
;         for (int n = 0; n < 2; ++n) {
;           const int cl = wc * 32 + n * 16 + fr2, cg = pn * 128 + cl;
;           float am2 = 0.f, am1 = 0.f;
;           if (R0 > 0) { am2 = bf2f(sAt[(R0 - 2) * AS + cl]); am1 = bf2f(sAt[(R0 - 1) * AS + cl]); }
; #pragma unroll
;           for (int j = 0; j < 4; ++j) {
;             const float a0 = acc[ai][0][m][n][j], b0 = acc[ai][1][m][n][j];
;             if (R0 > 0 || j >= 2) {
;               const float gv = gelu_tanh(bs[n] + w0[n] * am2 + w1[n] * am1 + w2[n] * a0) * b0;
;               ge.g[(size_t)(brow + R0 + j) * DFF + cg] = f2bf(gv);
;             } else {
;               ge.first_a[((size_t)pm * 2 + j) * DFF + cg] = sAt[(R0 + j) * AS + cl];
;               ge.first_b[((size_t)pm * 2 + j) * DFF + cg] = f2bf(b0);
;             }
;             if (R0 == 252 && j >= 2) ge.halo_a[((size_t)pm * 2 + (j - 2)) * DFF + cg] = sAt[(R0 + j) * AS + cl];
;             am2 = am1; am1 = a0;
	v_pk_mul_f32 v[248:249], v[240:241], v[240:241]
	v_pk_mul_f32 v[250:251], v[242:243], v[242:243]
	v_pk_mul_f32 v[182:183], v[244:245], v[244:245]
	v_pk_mul_f32 v[154:155], v[246:247], v[246:247]
	v_pk_fma_f32 v[248:249], v[248:249], s[52:53], v[180:181]
	v_pk_fma_f32 v[250:251], v[250:251], s[52:53], v[180:181]
	v_pk_fma_f32 v[182:183], v[182:183], s[52:53], v[180:181]
	v_pk_fma_f32 v[154:155], v[154:155], s[52:53], v[180:181]
	v_pk_mul_f32 v[248:249], v[240:241], v[248:249]
	v_pk_mul_f32 v[250:251], v[242:243], v[250:251]
	v_pk_mul_f32 v[182:183], v[244:245], v[182:183]
	v_pk_mul_f32 v[154:155], v[246:247], v[154:155]
	v_exp_f32_e32 v248, v248
	v_exp_f32_e32 v249, v249
	v_exp_f32_e32 v250, v250
	v_exp_f32_e32 v251, v251
	v_exp_f32_e32 v182, v182
	v_exp_f32_e32 v183, v183
	v_exp_f32_e32 v154, v154
	v_exp_f32_e32 v155, v155
	v_pk_add_f32 v[248:249], v[248:249], s[94:95]
	v_pk_add_f32 v[250:251], v[250:251], s[94:95]
	v_pk_add_f32 v[182:183], v[182:183], s[94:95]
	v_pk_add_f32 v[154:155], v[154:155], s[94:95]
	v_rcp_f32_e32 v248, v248
	v_rcp_f32_e32 v249, v249
	v_rcp_f32_e32 v250, v250
	v_rcp_f32_e32 v251, v251
	v_rcp_f32_e32 v182, v182
	v_rcp_f32_e32 v183, v183
	v_rcp_f32_e32 v154, v154
	v_rcp_f32_e32 v155, v155
	v_pk_mul_f32 v[240:241], v[240:241], v[248:249]
	v_pk_mul_f32 v[242:243], v[242:243], v[250:251]
	v_pk_mul_f32 v[244:245], v[244:245], v[182:183]
	v_pk_mul_f32 v[246:247], v[246:247], v[154:155]
	v_pk_mul_f32 v[240:241], v[240:241], v[36:37]
	v_pk_mul_f32 v[242:243], v[242:243], v[38:39]
	v_pk_mul_f32 v[244:245], v[244:245], v[32:33]
	v_pk_mul_f32 v[246:247], v[246:247], v[34:35]
	v_cvt_pk_bf16_f32 v248, v240, v241
	v_cvt_pk_bf16_f32 v249, v242, v243
	v_cvt_pk_bf16_f32 v250, v244, v245
	v_cvt_pk_bf16_f32 v251, v246, v247
	global_store_dwordx4 v153, v[248:251], s[0:1] sc1
	s_add_u32 s0, s0, 0xdc000
	s_addc_u32 s1, s1, 0
	s_waitcnt lgkmcnt(0)
	v_pk_fma_f32 v[240:241], v[200:201], v[28:29], v[208:209]
	v_pk_fma_f32 v[242:243], v[202:203], v[30:31], v[210:211]
	v_pk_fma_f32 v[244:245], v[204:205], v[24:25], v[212:213]
	v_pk_fma_f32 v[246:247], v[206:207], v[26:27], v[214:215]
	v_fmac_f32_dpp v240, v28, v192 row_shr:1 row_mask:0xf bank_mask:0xf
	v_fmac_f32_dpp v241, v29, v193 row_shr:1 row_mask:0xf bank_mask:0xf
	v_fmac_f32_dpp v242, v30, v194 row_shr:1 row_mask:0xf bank_mask:0xf
	v_fmac_f32_dpp v243, v31, v195 row_shr:1 row_mask:0xf bank_mask:0xf
	v_fmac_f32_dpp v244, v24, v196 row_shr:1 row_mask:0xf bank_mask:0xf
	v_fmac_f32_dpp v245, v25, v197 row_shr:1 row_mask:0xf bank_mask:0xf
	v_fmac_f32_dpp v246, v26, v198 row_shr:1 row_mask:0xf bank_mask:0xf
	v_fmac_f32_dpp v247, v27, v199 row_shr:1 row_mask:0xf bank_mask:0xf
	v_fmac_f32_dpp v240, v232, v216 row_ror:1 row_mask:0xf bank_mask:0xf
	v_fmac_f32_dpp v241, v233, v217 row_ror:1 row_mask:0xf bank_mask:0xf
	v_fmac_f32_dpp v242, v234, v218 row_ror:1 row_mask:0xf bank_mask:0xf
	v_fmac_f32_dpp v243, v235, v219 row_ror:1 row_mask:0xf bank_mask:0xf
	v_fmac_f32_dpp v244, v236, v220 row_ror:1 row_mask:0xf bank_mask:0xf
	v_fmac_f32_dpp v245, v237, v221 row_ror:1 row_mask:0xf bank_mask:0xf
	v_fmac_f32_dpp v246, v238, v222 row_ror:1 row_mask:0xf bank_mask:0xf
	v_fmac_f32_dpp v247, v239, v223 row_ror:1 row_mask:0xf bank_mask:0xf
	v_fmac_f32_dpp v240, v28, v184 row_shr:2 row_mask:0xf bank_mask:0xf
	v_fmac_f32_dpp v241, v29, v185 row_shr:2 row_mask:0xf bank_mask:0xf
	v_fmac_f32_dpp v242, v30, v186 row_shr:2 row_mask:0xf bank_mask:0xf
	v_fmac_f32_dpp v243, v31, v187 row_shr:2 row_mask:0xf bank_mask:0xf
	v_fmac_f32_dpp v244, v24, v188 row_shr:2 row_mask:0xf bank_mask:0xf
	v_fmac_f32_dpp v245, v25, v189 row_shr:2 row_mask:0xf bank_mask:0xf
	v_fmac_f32_dpp v246, v26, v190 row_shr:2 row_mask:0xf bank_mask:0xf
	v_fmac_f32_dpp v247, v27, v191 row_shr:2 row_mask:0xf bank_mask:0xf
	v_fmac_f32_dpp v240, v232, v224 row_ror:2 row_mask:0xf bank_mask:0xf
	v_fmac_f32_dpp v241, v233, v225 row_ror:2 row_mask:0xf bank_mask:0xf
	v_fmac_f32_dpp v242, v234, v226 row_ror:2 row_mask:0xf bank_mask:0xf
	v_fmac_f32_dpp v243, v235, v227 row_ror:2 row_mask:0xf bank_mask:0xf
	v_fmac_f32_dpp v244, v236, v228 row_ror:2 row_mask:0xf bank_mask:0xf
	v_fmac_f32_dpp v245, v237, v229 row_ror:2 row_mask:0xf bank_mask:0xf
	v_fmac_f32_dpp v246, v238, v230 row_ror:2 row_mask:0xf bank_mask:0xf
	v_fmac_f32_dpp v247, v239, v231 row_ror:2 row_mask:0xf bank_mask:0xf
	v_pk_mul_f32 v[248:249], v[240:241], v[240:241]
	v_pk_mul_f32 v[250:251], v[242:243], v[242:243]
	v_pk_mul_f32 v[182:183], v[244:245], v[244:245]
	v_pk_mul_f32 v[154:155], v[246:247], v[246:247]
	v_pk_fma_f32 v[248:249], v[248:249], s[52:53], v[180:181]
	v_pk_fma_f32 v[250:251], v[250:251], s[52:53], v[180:181]
	v_pk_fma_f32 v[182:183], v[182:183], s[52:53], v[180:181]
	v_pk_fma_f32 v[154:155], v[154:155], s[52:53], v[180:181]
	v_pk_mul_f32 v[248:249], v[240:241], v[248:249]
	v_pk_mul_f32 v[250:251], v[242:243], v[250:251]
	v_pk_mul_f32 v[182:183], v[244:245], v[182:183]
	v_pk_mul_f32 v[154:155], v[246:247], v[154:155]
	v_exp_f32_e32 v248, v248
	v_exp_f32_e32 v249, v249
	v_exp_f32_e32 v250, v250
	v_exp_f32_e32 v251, v251
	v_exp_f32_e32 v182, v182
	v_exp_f32_e32 v183, v183
	v_exp_f32_e32 v154, v154
	v_exp_f32_e32 v155, v155
	v_pk_add_f32 v[248:249], v[248:249], s[94:95]
	v_pk_add_f32 v[250:251], v[250:251], s[94:95]
	v_pk_add_f32 v[182:183], v[182:183], s[94:95]
	v_pk_add_f32 v[154:155], v[154:155], s[94:95]
	v_rcp_f32_e32 v248, v248
	v_rcp_f32_e32 v249, v249
	v_rcp_f32_e32 v250, v250
	v_rcp_f32_e32 v251, v251
	v_rcp_f32_e32 v182, v182
	v_rcp_f32_e32 v183, v183
	v_rcp_f32_e32 v154, v154
	v_rcp_f32_e32 v155, v155
	v_pk_mul_f32 v[240:241], v[240:241], v[248:249]
; DEV float bf2f(u16 h) { return __uint_as_float(((uint32_t)h) << 16); }
; DEV float gelu_tanh(float x) {
;   const float e = __builtin_amdgcn_exp2f(x * __builtin_fmaf(x * x, -0.10294324f, -2.3022082f));
;   return x * __builtin_amdgcn_rcpf(1.0f + e);
; }
; DEV void gemm_tile(const u16* __restrict__ A, const u16* __restrict__ Bt, u16* __restrict__ C, int N, int K,
;                    int brow, int bcol, unsigned char* smem, int epi, const GateEpi& ge) {
;     ...
;         const int R0 = ai * 128 + wr * 64 + m * 16 + fq2 * 4;
; #pragma unroll
;         for (int n = 0; n < 2; ++n) {
;           const int cl = wc * 32 + n * 16 + fr2, cg = pn * 128 + cl;
;           float am2 = 0.f, am1 = 0.f;
;           if (R0 > 0) { am2 = bf2f(sAt[(R0 - 2) * AS + cl]); am1 = bf2f(sAt[(R0 - 1) * AS + cl]); }
; #pragma unroll
;           for (int j = 0; j < 4; ++j) {
;             const float a0 = acc[ai][0][m][n][j], b0 = acc[ai][1][m][n][j];
;             if (R0 > 0 || j >= 2) {
;               const float gv = gelu_tanh(bs[n] + w0[n] * am2 + w1[n] * am1 + w2[n] * a0) * b0;
;               ge.g[(size_t)(brow + R0 + j) * DFF + cg] = f2bf(gv);
;             } else {
;               ge.first_a[((size_t)pm * 2 + j) * DFF + cg] = sAt[(R0 + j) * AS + cl];
;               ge.first_b[((size_t)pm * 2 + j) * DFF + cg] = f2bf(b0);
;             }
;             if (R0 == 252 && j >= 2) ge.halo_a[((size_t)pm * 2 + (j - 2)) * DFF + cg] = sAt[(R0 + j) * AS + cl];
;             am2 = am1; am1 = a0;
	v_pk_mul_f32 v[242:243], v[242:243], v[250:251]
	v_pk_mul_f32 v[244:245], v[244:245], v[182:183]
	v_pk_mul_f32 v[246:247], v[246:247], v[154:155]
	v_pk_mul_f32 v[240:241], v[240:241], v[56:57]
	v_pk_mul_f32 v[242:243], v[242:243], v[58:59]
	v_pk_mul_f32 v[244:245], v[244:245], v[60:61]
	v_pk_mul_f32 v[246:247], v[246:247], v[62:63]
	v_cvt_pk_bf16_f32 v248, v240, v241
	v_cvt_pk_bf16_f32 v249, v242, v243
	v_cvt_pk_bf16_f32 v250, v244, v245
	v_cvt_pk_bf16_f32 v251, v246, v247
	global_store_dwordx4 v153, v[248:251], s[0:1] sc1
	s_add_u32 s0, s0, 0x2c000
	s_addc_u32 s1, s1, 0
	v_pk_fma_f32 v[240:241], v[200:201], v[20:21], v[208:209]
	v_pk_fma_f32 v[242:243], v[202:203], v[22:23], v[210:211]
	v_pk_fma_f32 v[244:245], v[204:205], v[16:17], v[212:213]
	v_pk_fma_f32 v[246:247], v[206:207], v[18:19], v[214:215]
	v_fmac_f32_dpp v240, v20, v192 row_shr:1 row_mask:0xf bank_mask:0xf
	v_fmac_f32_dpp v241, v21, v193 row_shr:1 row_mask:0xf bank_mask:0xf
	v_fmac_f32_dpp v242, v22, v194 row_shr:1 row_mask:0xf bank_mask:0xf
	v_fmac_f32_dpp v243, v23, v195 row_shr:1 row_mask:0xf bank_mask:0xf
	v_fmac_f32_dpp v244, v16, v196 row_shr:1 row_mask:0xf bank_mask:0xf
	v_fmac_f32_dpp v245, v17, v197 row_shr:1 row_mask:0xf bank_mask:0xf
	v_fmac_f32_dpp v246, v18, v198 row_shr:1 row_mask:0xf bank_mask:0xf
	v_fmac_f32_dpp v247, v19, v199 row_shr:1 row_mask:0xf bank_mask:0xf
	v_fmac_f32_dpp v240, v28, v216 row_ror:1 row_mask:0xf bank_mask:0xf
	v_fmac_f32_dpp v241, v29, v217 row_ror:1 row_mask:0xf bank_mask:0xf
	v_fmac_f32_dpp v242, v30, v218 row_ror:1 row_mask:0xf bank_mask:0xf
	v_fmac_f32_dpp v243, v31, v219 row_ror:1 row_mask:0xf bank_mask:0xf
	v_fmac_f32_dpp v244, v24, v220 row_ror:1 row_mask:0xf bank_mask:0xf
	v_fmac_f32_dpp v245, v25, v221 row_ror:1 row_mask:0xf bank_mask:0xf
	v_fmac_f32_dpp v246, v26, v222 row_ror:1 row_mask:0xf bank_mask:0xf
	v_fmac_f32_dpp v247, v27, v223 row_ror:1 row_mask:0xf bank_mask:0xf
	v_fmac_f32_dpp v240, v20, v184 row_shr:2 row_mask:0xf bank_mask:0xf
	v_fmac_f32_dpp v241, v21, v185 row_shr:2 row_mask:0xf bank_mask:0xf
	v_fmac_f32_dpp v242, v22, v186 row_shr:2 row_mask:0xf bank_mask:0xf
	v_fmac_f32_dpp v243, v23, v187 row_shr:2 row_mask:0xf bank_mask:0xf
	v_fmac_f32_dpp v244, v16, v188 row_shr:2 row_mask:0xf bank_mask:0xf
	v_fmac_f32_dpp v245, v17, v189 row_shr:2 row_mask:0xf bank_mask:0xf
	v_fmac_f32_dpp v246, v18, v190 row_shr:2 row_mask:0xf bank_mask:0xf
	v_fmac_f32_dpp v247, v19, v191 row_shr:2 row_mask:0xf bank_mask:0xf
	v_fmac_f32_dpp v240, v28, v224 row_ror:2 row_mask:0xf bank_mask:0xf
	v_fmac_f32_dpp v241, v29, v225 row_ror:2 row_mask:0xf bank_mask:0xf
	v_fmac_f32_dpp v242, v30, v226 row_ror:2 row_mask:0xf bank_mask:0xf
	v_fmac_f32_dpp v243, v31, v227 row_ror:2 row_mask:0xf bank_mask:0xf
	v_fmac_f32_dpp v244, v24, v228 row_ror:2 row_mask:0xf bank_mask:0xf
	v_fmac_f32_dpp v245, v25, v229 row_ror:2 row_mask:0xf bank_mask:0xf
	v_fmac_f32_dpp v246, v26, v230 row_ror:2 row_mask:0xf bank_mask:0xf
	v_fmac_f32_dpp v247, v27, v231 row_ror:2 row_mask:0xf bank_mask:0xf
	v_pk_mul_f32 v[248:249], v[240:241], v[240:241]
	v_pk_mul_f32 v[250:251], v[242:243], v[242:243]
	v_pk_mul_f32 v[182:183], v[244:245], v[244:245]
	v_pk_mul_f32 v[154:155], v[246:247], v[246:247]
	v_pk_fma_f32 v[248:249], v[248:249], s[52:53], v[180:181]
	v_pk_fma_f32 v[250:251], v[250:251], s[52:53], v[180:181]
	v_pk_fma_f32 v[182:183], v[182:183], s[52:53], v[180:181]
	v_pk_fma_f32 v[154:155], v[154:155], s[52:53], v[180:181]
	v_pk_mul_f32 v[248:249], v[240:241], v[248:249]
	v_pk_mul_f32 v[250:251], v[242:243], v[250:251]
	v_pk_mul_f32 v[182:183], v[244:245], v[182:183]
	v_pk_mul_f32 v[154:155], v[246:247], v[154:155]
	v_exp_f32_e32 v248, v248
	v_exp_f32_e32 v249, v249
	v_exp_f32_e32 v250, v250
	v_exp_f32_e32 v251, v251
	v_exp_f32_e32 v182, v182
	v_exp_f32_e32 v183, v183
	v_exp_f32_e32 v154, v154
	v_exp_f32_e32 v155, v155
	v_pk_add_f32 v[248:249], v[248:249], s[94:95]
	v_pk_add_f32 v[250:251], v[250:251], s[94:95]
	v_pk_add_f32 v[182:183], v[182:183], s[94:95]
	v_pk_add_f32 v[154:155], v[154:155], s[94:95]
	v_rcp_f32_e32 v248, v248
	v_rcp_f32_e32 v249, v249
	v_rcp_f32_e32 v250, v250
	v_rcp_f32_e32 v251, v251
	v_rcp_f32_e32 v182, v182
	v_rcp_f32_e32 v183, v183
	v_rcp_f32_e32 v154, v154
	v_rcp_f32_e32 v155, v155
	v_pk_mul_f32 v[240:241], v[240:241], v[248:249]
	v_pk_mul_f32 v[242:243], v[242:243], v[250:251]
	v_pk_mul_f32 v[244:245], v[244:245], v[182:183]
	v_pk_mul_f32 v[246:247], v[246:247], v[154:155]
	v_pk_mul_f32 v[240:241], v[240:241], v[64:65]
	v_pk_mul_f32 v[242:243], v[242:243], v[66:67]
	v_pk_mul_f32 v[244:245], v[244:245], v[72:73]
	v_pk_mul_f32 v[246:247], v[246:247], v[74:75]
	v_cvt_pk_bf16_f32 v248, v240, v241
	v_cvt_pk_bf16_f32 v249, v242, v243
	v_cvt_pk_bf16_f32 v250, v244, v245
	v_cvt_pk_bf16_f32 v251, v246, v247
	global_store_dwordx4 v153, v[248:251], s[0:1] sc1
	s_add_u32 s0, s0, 0x2c000
	s_addc_u32 s1, s1, 0
	v_pk_fma_f32 v[240:241], v[200:201], v[12:13], v[208:209]
	v_pk_fma_f32 v[242:243], v[202:203], v[14:15], v[210:211]
	v_pk_fma_f32 v[244:245], v[204:205], v[8:9], v[212:213]
	v_pk_fma_f32 v[246:247], v[206:207], v[10:11], v[214:215]
	v_fmac_f32_dpp v240, v12, v192 row_shr:1 row_mask:0xf bank_mask:0xf
	v_fmac_f32_dpp v241, v13, v193 row_shr:1 row_mask:0xf bank_mask:0xf
	v_fmac_f32_dpp v242, v14, v194 row_shr:1 row_mask:0xf bank_mask:0xf
	v_fmac_f32_dpp v243, v15, v195 row_shr:1 row_mask:0xf bank_mask:0xf
	v_fmac_f32_dpp v244, v8, v196 row_shr:1 row_mask:0xf bank_mask:0xf
	v_fmac_f32_dpp v245, v9, v197 row_shr:1 row_mask:0xf bank_mask:0xf
	v_fmac_f32_dpp v246, v10, v198 row_shr:1 row_mask:0xf bank_mask:0xf
	v_fmac_f32_dpp v247, v11, v199 row_shr:1 row_mask:0xf bank_mask:0xf
; DEV float bf2f(u16 h) { return __uint_as_float(((uint32_t)h) << 16); }
; DEV float gelu_tanh(float x) {
;   const float e = __builtin_amdgcn_exp2f(x * __builtin_fmaf(x * x, -0.10294324f, -2.3022082f));
;   return x * __builtin_amdgcn_rcpf(1.0f + e);
; }
; DEV void gemm_tile(const u16* __restrict__ A, const u16* __restrict__ Bt, u16* __restrict__ C, int N, int K,
;                    int brow, int bcol, unsigned char* smem, int epi, const GateEpi& ge) {
;     ...
;         const int R0 = ai * 128 + wr * 64 + m * 16 + fq2 * 4;
; #pragma unroll
;         for (int n = 0; n < 2; ++n) {
;           const int cl = wc * 32 + n * 16 + fr2, cg = pn * 128 + cl;
;           float am2 = 0.f, am1 = 0.f;
;           if (R0 > 0) { am2 = bf2f(sAt[(R0 - 2) * AS + cl]); am1 = bf2f(sAt[(R0 - 1) * AS + cl]); }
; #pragma unroll
;           for (int j = 0; j < 4; ++j) {
;             const float a0 = acc[ai][0][m][n][j], b0 = acc[ai][1][m][n][j];
;             if (R0 > 0 || j >= 2) {
;               const float gv = gelu_tanh(bs[n] + w0[n] * am2 + w1[n] * am1 + w2[n] * a0) * b0;
;               ge.g[(size_t)(brow + R0 + j) * DFF + cg] = f2bf(gv);
;             } else {
;               ge.first_a[((size_t)pm * 2 + j) * DFF + cg] = sAt[(R0 + j) * AS + cl];
;               ge.first_b[((size_t)pm * 2 + j) * DFF + cg] = f2bf(b0);
;             }
;             if (R0 == 252 && j >= 2) ge.halo_a[((size_t)pm * 2 + (j - 2)) * DFF + cg] = sAt[(R0 + j) * AS + cl];
;             am2 = am1; am1 = a0;
	v_fmac_f32_dpp v240, v20, v216 row_ror:1 row_mask:0xf bank_mask:0xf
	v_fmac_f32_dpp v241, v21, v217 row_ror:1 row_mask:0xf bank_mask:0xf
	v_fmac_f32_dpp v242, v22, v218 row_ror:1 row_mask:0xf bank_mask:0xf
	v_fmac_f32_dpp v243, v23, v219 row_ror:1 row_mask:0xf bank_mask:0xf
	v_fmac_f32_dpp v244, v16, v220 row_ror:1 row_mask:0xf bank_mask:0xf
	v_fmac_f32_dpp v245, v17, v221 row_ror:1 row_mask:0xf bank_mask:0xf
	v_fmac_f32_dpp v246, v18, v222 row_ror:1 row_mask:0xf bank_mask:0xf
	v_fmac_f32_dpp v247, v19, v223 row_ror:1 row_mask:0xf bank_mask:0xf
	v_fmac_f32_dpp v240, v12, v184 row_shr:2 row_mask:0xf bank_mask:0xf
	v_fmac_f32_dpp v241, v13, v185 row_shr:2 row_mask:0xf bank_mask:0xf
	v_fmac_f32_dpp v242, v14, v186 row_shr:2 row_mask:0xf bank_mask:0xf
	v_fmac_f32_dpp v243, v15, v187 row_shr:2 row_mask:0xf bank_mask:0xf
	v_fmac_f32_dpp v244, v8, v188 row_shr:2 row_mask:0xf bank_mask:0xf
	v_fmac_f32_dpp v245, v9, v189 row_shr:2 row_mask:0xf bank_mask:0xf
	v_fmac_f32_dpp v246, v10, v190 row_shr:2 row_mask:0xf bank_mask:0xf
	v_fmac_f32_dpp v247, v11, v191 row_shr:2 row_mask:0xf bank_mask:0xf
	v_fmac_f32_dpp v240, v20, v224 row_ror:2 row_mask:0xf bank_mask:0xf
	v_fmac_f32_dpp v241, v21, v225 row_ror:2 row_mask:0xf bank_mask:0xf
	v_fmac_f32_dpp v242, v22, v226 row_ror:2 row_mask:0xf bank_mask:0xf
	v_fmac_f32_dpp v243, v23, v227 row_ror:2 row_mask:0xf bank_mask:0xf
	v_fmac_f32_dpp v244, v16, v228 row_ror:2 row_mask:0xf bank_mask:0xf
	v_fmac_f32_dpp v245, v17, v229 row_ror:2 row_mask:0xf bank_mask:0xf
	v_fmac_f32_dpp v246, v18, v230 row_ror:2 row_mask:0xf bank_mask:0xf
	v_fmac_f32_dpp v247, v19, v231 row_ror:2 row_mask:0xf bank_mask:0xf
	v_pk_mul_f32 v[248:249], v[240:241], v[240:241]
	v_pk_mul_f32 v[250:251], v[242:243], v[242:243]
	v_pk_mul_f32 v[182:183], v[244:245], v[244:245]
	v_pk_mul_f32 v[154:155], v[246:247], v[246:247]
	v_pk_fma_f32 v[248:249], v[248:249], s[52:53], v[180:181]
	v_pk_fma_f32 v[250:251], v[250:251], s[52:53], v[180:181]
	v_pk_fma_f32 v[182:183], v[182:183], s[52:53], v[180:181]
	v_pk_fma_f32 v[154:155], v[154:155], s[52:53], v[180:181]
	v_pk_mul_f32 v[248:249], v[240:241], v[248:249]
	v_pk_mul_f32 v[250:251], v[242:243], v[250:251]
	v_pk_mul_f32 v[182:183], v[244:245], v[182:183]
	v_pk_mul_f32 v[154:155], v[246:247], v[154:155]
	v_exp_f32_e32 v248, v248
	v_exp_f32_e32 v249, v249
	v_exp_f32_e32 v250, v250
	v_exp_f32_e32 v251, v251
	v_exp_f32_e32 v182, v182
	v_exp_f32_e32 v183, v183
	v_exp_f32_e32 v154, v154
	v_exp_f32_e32 v155, v155
	v_pk_add_f32 v[248:249], v[248:249], s[94:95]
	v_pk_add_f32 v[250:251], v[250:251], s[94:95]
	v_pk_add_f32 v[182:183], v[182:183], s[94:95]
	v_pk_add_f32 v[154:155], v[154:155], s[94:95]
	v_rcp_f32_e32 v248, v248
	v_rcp_f32_e32 v249, v249
	v_rcp_f32_e32 v250, v250
	v_rcp_f32_e32 v251, v251
	v_rcp_f32_e32 v182, v182
	v_rcp_f32_e32 v183, v183
	v_rcp_f32_e32 v154, v154
	v_rcp_f32_e32 v155, v155
	v_pk_mul_f32 v[240:241], v[240:241], v[248:249]
	v_pk_mul_f32 v[242:243], v[242:243], v[250:251]
	v_pk_mul_f32 v[244:245], v[244:245], v[182:183]
	v_pk_mul_f32 v[246:247], v[246:247], v[154:155]
	v_pk_mul_f32 v[240:241], v[240:241], v[76:77]
	v_pk_mul_f32 v[242:243], v[242:243], v[78:79]
	v_pk_mul_f32 v[244:245], v[244:245], v[80:81]
	v_pk_mul_f32 v[246:247], v[246:247], v[82:83]
	v_cvt_pk_bf16_f32 v248, v240, v241
	v_cvt_pk_bf16_f32 v249, v242, v243
	v_cvt_pk_bf16_f32 v250, v244, v245
	v_cvt_pk_bf16_f32 v251, v246, v247
	global_store_dwordx4 v153, v[248:251], s[0:1] sc1
	s_add_u32 s0, s0, 0x2c000
	s_addc_u32 s1, s1, 0
	v_pk_fma_f32 v[240:241], v[200:201], v[4:5], v[208:209]
	v_pk_fma_f32 v[242:243], v[202:203], v[6:7], v[210:211]
	v_pk_fma_f32 v[244:245], v[204:205], v[0:1], v[212:213]
	v_pk_fma_f32 v[246:247], v[206:207], v[2:3], v[214:215]
	v_fmac_f32_dpp v240, v4, v192 row_shr:1 row_mask:0xf bank_mask:0xf
	v_fmac_f32_dpp v241, v5, v193 row_shr:1 row_mask:0xf bank_mask:0xf
	v_fmac_f32_dpp v242, v6, v194 row_shr:1 row_mask:0xf bank_mask:0xf
	v_fmac_f32_dpp v243, v7, v195 row_shr:1 row_mask:0xf bank_mask:0xf
; DEV float bf2f(u16 h) { return __uint_as_float(((uint32_t)h) << 16); }
; DEV void gemm_tile(const u16* __restrict__ A, const u16* __restrict__ Bt, u16* __restrict__ C, int N, int K,
;                    int brow, int bcol, unsigned char* smem, int epi, const GateEpi& ge) {
;     ...
;         const int R0 = ai * 128 + wr * 64 + m * 16 + fq2 * 4;
; #pragma unroll
;         for (int n = 0; n < 2; ++n) {
;           const int cl = wc * 32 + n * 16 + fr2, cg = pn * 128 + cl;
;           float am2 = 0.f, am1 = 0.f;
;           if (R0 > 0) { am2 = bf2f(sAt[(R0 - 2) * AS + cl]); am1 = bf2f(sAt[(R0 - 1) * AS + cl]); }
; #pragma unroll
;           for (int j = 0; j < 4; ++j) {
;             const float a0 = acc[ai][0][m][n][j], b0 = acc[ai][1][m][n][j];
;             if (R0 > 0 || j >= 2) {
;               const float gv = gelu_tanh(bs[n] + w0[n] * am2 + w1[n] * am1 + w2[n] * a0) * b0;
;               ge.g[(size_t)(brow + R0 + j) * DFF + cg] = f2bf(gv);
;             } else {
;               ge.first_a[((size_t)pm * 2 + j) * DFF + cg] = sAt[(R0 + j) * AS + cl];
;               ge.first_b[((size_t)pm * 2 + j) * DFF + cg] = f2bf(b0);
;             }
;             if (R0 == 252 && j >= 2) ge.halo_a[((size_t)pm * 2 + (j - 2)) * DFF + cg] = sAt[(R0 + j) * AS + cl];
;             am2 = am1; am1 = a0;
	v_fmac_f32_dpp v244, v0, v196 row_shr:1 row_mask:0xf bank_mask:0xf
	v_fmac_f32_dpp v245, v1, v197 row_shr:1 row_mask:0xf bank_mask:0xf
	v_fmac_f32_dpp v246, v2, v198 row_shr:1 row_mask:0xf bank_mask:0xf
	v_fmac_f32_dpp v247, v3, v199 row_shr:1 row_mask:0xf bank_mask:0xf
	v_fmac_f32_dpp v240, v12, v216 row_ror:1 row_mask:0xf bank_mask:0xf
	v_fmac_f32_dpp v241, v13, v217 row_ror:1 row_mask:0xf bank_mask:0xf
	v_fmac_f32_dpp v242, v14, v218 row_ror:1 row_mask:0xf bank_mask:0xf
	v_fmac_f32_dpp v243, v15, v219 row_ror:1 row_mask:0xf bank_mask:0xf
	v_fmac_f32_dpp v244, v8, v220 row_ror:1 row_mask:0xf bank_mask:0xf
	v_fmac_f32_dpp v245, v9, v221 row_ror:1 row_mask:0xf bank_mask:0xf
	v_fmac_f32_dpp v246, v10, v222 row_ror:1 row_mask:0xf bank_mask:0xf
	v_fmac_f32_dpp v247, v11, v223 row_ror:1 row_mask:0xf bank_mask:0xf
	v_fmac_f32_dpp v240, v4, v184 row_shr:2 row_mask:0xf bank_mask:0xf
	v_fmac_f32_dpp v241, v5, v185 row_shr:2 row_mask:0xf bank_mask:0xf
	v_fmac_f32_dpp v242, v6, v186 row_shr:2 row_mask:0xf bank_mask:0xf
	v_fmac_f32_dpp v243, v7, v187 row_shr:2 row_mask:0xf bank_mask:0xf
	v_fmac_f32_dpp v244, v0, v188 row_shr:2 row_mask:0xf bank_mask:0xf
	v_fmac_f32_dpp v245, v1, v189 row_shr:2 row_mask:0xf bank_mask:0xf
	v_fmac_f32_dpp v246, v2, v190 row_shr:2 row_mask:0xf bank_mask:0xf
	v_fmac_f32_dpp v247, v3, v191 row_shr:2 row_mask:0xf bank_mask:0xf
	v_fmac_f32_dpp v240, v12, v224 row_ror:2 row_mask:0xf bank_mask:0xf
	v_fmac_f32_dpp v241, v13, v225 row_ror:2 row_mask:0xf bank_mask:0xf
	v_fmac_f32_dpp v242, v14, v226 row_ror:2 row_mask:0xf bank_mask:0xf
	v_fmac_f32_dpp v243, v15, v227 row_ror:2 row_mask:0xf bank_mask:0xf
	v_fmac_f32_dpp v244, v8, v228 row_ror:2 row_mask:0xf bank_mask:0xf
	v_fmac_f32_dpp v245, v9, v229 row_ror:2 row_mask:0xf bank_mask:0xf
	v_fmac_f32_dpp v246, v10, v230 row_ror:2 row_mask:0xf bank_mask:0xf
	v_fmac_f32_dpp v247, v11, v231 row_ror:2 row_mask:0xf bank_mask:0xf
	v_pk_mul_f32 v[248:249], v[240:241], v[240:241]
	v_pk_mul_f32 v[250:251], v[242:243], v[242:243]
	v_pk_mul_f32 v[182:183], v[244:245], v[244:245]
	v_pk_mul_f32 v[154:155], v[246:247], v[246:247]
	v_pk_fma_f32 v[248:249], v[248:249], s[52:53], v[180:181]
	v_pk_fma_f32 v[250:251], v[250:251], s[52:53], v[180:181]
	v_pk_fma_f32 v[182:183], v[182:183], s[52:53], v[180:181]
	v_pk_fma_f32 v[154:155], v[154:155], s[52:53], v[180:181]
	v_pk_mul_f32 v[248:249], v[240:241], v[248:249]
	v_pk_mul_f32 v[250:251], v[242:243], v[250:251]
	v_pk_mul_f32 v[182:183], v[244:245], v[182:183]
	v_pk_mul_f32 v[154:155], v[246:247], v[154:155]
	v_exp_f32_e32 v248, v248
	v_exp_f32_e32 v249, v249
	v_exp_f32_e32 v250, v250
	v_exp_f32_e32 v251, v251
	v_exp_f32_e32 v182, v182
	v_exp_f32_e32 v183, v183
	v_exp_f32_e32 v154, v154
	v_exp_f32_e32 v155, v155
	v_pk_add_f32 v[248:249], v[248:249], s[94:95]
	v_pk_add_f32 v[250:251], v[250:251], s[94:95]
	v_pk_add_f32 v[182:183], v[182:183], s[94:95]
	v_pk_add_f32 v[154:155], v[154:155], s[94:95]
	v_rcp_f32_e32 v248, v248
	v_rcp_f32_e32 v249, v249
	v_rcp_f32_e32 v250, v250
	v_rcp_f32_e32 v251, v251
	v_rcp_f32_e32 v182, v182
	v_rcp_f32_e32 v183, v183
	v_rcp_f32_e32 v154, v154
	v_rcp_f32_e32 v155, v155
	v_pk_mul_f32 v[240:241], v[240:241], v[248:249]
	v_pk_mul_f32 v[242:243], v[242:243], v[250:251]
	v_pk_mul_f32 v[244:245], v[244:245], v[182:183]
	v_pk_mul_f32 v[246:247], v[246:247], v[154:155]
	v_pk_mul_f32 v[240:241], v[240:241], v[88:89]
	v_pk_mul_f32 v[242:243], v[242:243], v[90:91]
	v_pk_mul_f32 v[244:245], v[244:245], v[92:93]
	v_pk_mul_f32 v[246:247], v[246:247], v[94:95]
	v_cvt_pk_bf16_f32 v248, v240, v241
	v_cvt_pk_bf16_f32 v249, v242, v243
	v_cvt_pk_bf16_f32 v250, v244, v245
	v_cvt_pk_bf16_f32 v251, v246, v247
	global_store_dwordx4 v153, v[248:251], s[0:1] sc1
	s_cmp_lg_u32 s34, 1
	s_cbranch_scc1 .Lgate_end_0
	s_mov_b32 exec_lo, 0xc000c000
	s_mov_b32 exec_hi, 0xc000c000
	v_cvt_pk_bf16_f32 v240, v4, v5
	v_cvt_pk_bf16_f32 v241, v6, v7
	v_cvt_pk_bf16_f32 v242, v0, v1
	v_cvt_pk_bf16_f32 v243, v2, v3
	global_store_dwordx4 v153, v[240:243], s[54:55] sc1
	s_mov_b64 exec, -1
